# SEL band loop: first ring stage (two blocks) issued right after the importance barrier so its DMA latency hides under the top-k search
# baseline (speedup 1.0000x reference)
; template <bool SEL> ...
;     ...
;     __syncthreads();
; #pragma unroll
;     for (int pi = 0; pi < 2; ++pi) if (pi < n) { const unsigned char* blk = KV + (size_t)(jhi - pi) * SLOTB; dma_block(lds3, pi, wu, blk, soff, blk + 8192, soff); }
; __device__ __forceinline__ void unitA(unsigned char* lds, PG8_LAS unsigned char* lds3, const Args& a, int b, int g, int T) {
;     ...
;     for (int rep_ = 0; rep_ < REP_TOPK; ++rep_) {
;         const int qi = 8 * w + (lane >> 3), gq = lane & 7;
;         unsigned m16 = 0u;
;         if (T <= 15) {
; #pragma unroll
;             for (int i = 0; i < 16; ++i) m16 |= (16 * gq + i <= T) ? (1u << i) : 0u;
;         } else {
;             unsigned u[16];
; #pragma unroll
;             for (int i = 0; i < 16; ++i) { const int j = 16 * gq + i; u[i] = (j >= 1 && j <= T - 2) ? __float_as_uint(imp[qi * IMP_LD + j]) : 0u; }
.LBB0_2430:
	s_add_i32 s93, s0, -2
	s_add_i32 s46, s0, -1
	v_lshlrev_b32_e32 v19, 4, v146
	s_mov_b64 s[8:9], -1
	s_barrier
	s_cmp_lt_i32 s0, 0
	s_cbranch_scc1 .Lsel_pf_done
	v_readlane_b32 s98, v253, 44
	v_readlane_b32 s99, v253, 45
	s_lshl_b32 s100, s36, 21
	s_add_u32 s98, s98, s100
	s_addc_u32 s99, s99, 0
	s_lshl_b32 s100, s0, 14
	s_add_u32 s100, s98, s100
	s_addc_u32 s101, s99, 0
	v_lshl_add_u64 v[232:233], s[100:101], 0, v[0:1]
	s_mov_b32 s100, 0xffffc000
	s_mov_b32 s101, -1
	v_lshl_add_u64 v[236:237], v[232:233], 0, s[100:101]
	s_mov_b64 s[100:101], 0x2000
	v_lshl_add_u64 v[234:235], v[232:233], 0, s[100:101]
	v_lshl_add_u64 v[238:239], v[236:237], 0, s[100:101]
	s_mov_b32 s98, m0
	s_mov_b32 m0, s95
	s_nop 0
	global_load_lds_dwordx4 v[232:233], off
	s_add_i32 m0, s95, 0x2000
	s_nop 0
	global_load_lds_dwordx4 v[234:235], off
	s_cmp_lt_i32 s0, 1
	s_cbranch_scc1 .Lsel_pf_one
	s_add_i32 m0, s95, 0x4000
	s_nop 0
	global_load_lds_dwordx4 v[236:237], off
	s_add_i32 m0, s95, 0x6000
	s_nop 0
	global_load_lds_dwordx4 v[238:239], off
.Lsel_pf_one:
	s_mov_b32 m0, s98
.Lsel_pf_done:
	s_cmp_gt_i32 s0, 15
	s_cbranch_scc0 .LBB0_2466
	v_mul_lo_u32 v52, v145, s66
	v_add_u32_e32 v52, s65, v52
	v_cmp_ne_u32_e64 s[8:9], 0, v146
	v_cmp_ge_i32_e64 s[10:11], s93, v19
	v_mov_b32_e32 v66, 0
	v_cmp_eq_u32_e32 vcc, 0, v146
	s_and_b64 s[10:11], s[8:9], s[10:11]
	v_lshl_add_u32 v76, v19, 2, v52
	v_mov_b32_e32 v67, 0
	s_and_saveexec_b64 s[8:9], s[10:11]
	ds_read_b32 v67, v76
	s_or_b64 exec, exec, s[8:9]
	v_cmp_gt_i32_e64 s[8:9], s93, v19
	s_and_saveexec_b64 s[10:11], s[8:9]
	ds_read_b32 v66, v76 offset:4
	s_or_b64 exec, exec, s[10:11]
	v_or_b32_e32 v52, 2, v19
	v_cmp_ge_i32_e64 s[10:11], s93, v52
	v_mov_b32_e32 v68, 0
	v_mov_b32_e32 v69, 0
	s_and_saveexec_b64 s[12:13], s[10:11]
	ds_read_b32 v69, v76 offset:8
	s_or_b64 exec, exec, s[12:13]
	v_or_b32_e32 v53, 3, v19
	v_cmp_ge_i32_e64 s[10:11], s93, v53
	s_and_saveexec_b64 s[12:13], s[10:11]
	ds_read_b32 v68, v76 offset:12
	s_or_b64 exec, exec, s[12:13]
	v_or_b32_e32 v54, 4, v19
	v_cmp_ge_i32_e64 s[10:11], s93, v54
	v_mov_b32_e32 v70, 0
	v_mov_b32_e32 v71, 0
	s_and_saveexec_b64 s[12:13], s[10:11]
	ds_read_b32 v71, v76 offset:16
	s_or_b64 exec, exec, s[12:13]
	v_or_b32_e32 v55, 5, v19
	v_cmp_ge_i32_e64 s[10:11], s93, v55
	s_and_saveexec_b64 s[12:13], s[10:11]
	ds_read_b32 v70, v76 offset:20
	s_or_b64 exec, exec, s[12:13]
	v_or_b32_e32 v56, 6, v19
	v_cmp_ge_i32_e64 s[10:11], s93, v56
	v_mov_b32_e32 v72, 0
	v_mov_b32_e32 v73, 0
	s_and_saveexec_b64 s[12:13], s[10:11]
	ds_read_b32 v73, v76 offset:24
	s_or_b64 exec, exec, s[12:13]
	v_or_b32_e32 v57, 7, v19
	v_cmp_ge_i32_e64 s[10:11], s93, v57
	s_and_saveexec_b64 s[12:13], s[10:11]
	ds_read_b32 v72, v76 offset:28
	s_or_b64 exec, exec, s[12:13]
	v_or_b32_e32 v58, 8, v19
	v_cmp_ge_i32_e64 s[10:11], s93, v58
	v_mov_b32_e32 v74, 0
	v_mov_b32_e32 v75, 0
	s_and_saveexec_b64 s[12:13], s[10:11]
	ds_read_b32 v75, v76 offset:32
	s_or_b64 exec, exec, s[12:13]
	v_or_b32_e32 v59, 9, v19
	v_cmp_ge_i32_e64 s[10:11], s93, v59
	s_and_saveexec_b64 s[12:13], s[10:11]
	ds_read_b32 v74, v76 offset:36
	s_or_b64 exec, exec, s[12:13]
	v_or_b32_e32 v60, 10, v19
	v_cmp_ge_i32_e64 s[10:11], s93, v60
	v_mov_b32_e32 v77, 0
	v_mov_b32_e32 v78, 0
	s_and_saveexec_b64 s[12:13], s[10:11]
	ds_read_b32 v78, v76 offset:40
	s_or_b64 exec, exec, s[12:13]
	v_or_b32_e32 v61, 11, v19
	v_cmp_ge_i32_e64 s[10:11], s93, v61
	s_and_saveexec_b64 s[12:13], s[10:11]
	ds_read_b32 v77, v76 offset:44
	s_or_b64 exec, exec, s[12:13]
	v_or_b32_e32 v62, 12, v19
	v_cmp_ge_i32_e64 s[10:11], s93, v62
	v_mov_b32_e32 v80, 0
	v_mov_b32_e32 v81, 0
	s_and_saveexec_b64 s[12:13], s[10:11]
	ds_read_b32 v81, v76 offset:48
	s_or_b64 exec, exec, s[12:13]
	v_or_b32_e32 v63, 13, v19
	v_cmp_ge_i32_e64 s[10:11], s93, v63
	s_and_saveexec_b64 s[12:13], s[10:11]
	ds_read_b32 v80, v76 offset:52
	s_or_b64 exec, exec, s[12:13]
	v_or_b32_e32 v64, 14, v19
	v_cmp_ge_i32_e64 s[10:11], s93, v64
	v_mov_b32_e32 v79, 0
	v_mov_b32_e32 v82, 0
	s_and_saveexec_b64 s[12:13], s[10:11]
	ds_read_b32 v82, v76 offset:56
	s_or_b64 exec, exec, s[12:13]
	v_or_b32_e32 v65, 15, v19
	v_cmp_ge_i32_e64 s[10:11], s93, v65
	s_and_saveexec_b64 s[12:13], s[10:11]
	ds_read_b32 v79, v76 offset:60
	s_mov_b32 s2, s46
	v_writelane_b32 v252, s36, 4
	s_mov_b64 s[96:97], s[80:81]
	v_writelane_b32 v252, s87, 5
	s_or_b64 exec, exec, s[12:13]
	v_mov_b32_e32 v76, 0
	s_mov_b32 s1, 30

; #define GATE(br, cg_) fsigmoid(gatev[br][cg_])
; template <bool SEL> ...
;     ...
;     __syncthreads();
; #pragma unroll
;     for (int pi = 0; pi < 2; ++pi) if (pi < n) { const unsigned char* blk = KV + (size_t)(jhi - pi) * SLOTB; dma_block(lds3, pi, wu, blk, soff, blk + 8192, soff); }
; __device__ __forceinline__ void unitA(unsigned char* lds, PG8_LAS unsigned char* lds3, const Args& a, int b, int g, int T) {
;     ...
;         const unsigned hi = (unsigned)__builtin_amdgcn_update_dpp(0, (int)m16, 0xB1, 0xF, 0xF, true);
;         if ((gq & 1) == 0) selm[qi * 4 + (gq >> 1)] = m16 | (hi << 16);
;     }
;     __syncthreads();
; #pragma unroll
;     for (int cg_ = 0; cg_ < 2; ++cg_) { const float gsc = GATE(0, cg_);
; #pragma unroll
;         for (int df = 0; df < 4; ++df) stash[(cg_ * 4 + df) * 512 + tid] = oc[cg_][df] * gsc; }
;     unsigned long long sw[2][2];
; #pragma unroll
;     for (int cg_ = 0; cg_ < 2; ++cg_) { const unsigned* sp = selm + (8 * w + 4 * cg_ + (c >> 2)) * 4;
;         sw[cg_][0] = (unsigned long long)sp[0] | ((unsigned long long)sp[1] << 32); sw[cg_][1] = (unsigned long long)sp[2] | ((unsigned long long)sp[3] << 32); }
.LBB0_2468:
	v_and_b32_e32 v19, 1, v133
	v_cmp_eq_u32_e32 vcc, 0, v19
	s_nop 0
	v_mov_b32_dpp v19, v52 quad_perm:[1,0,3,2] row_mask:0xf bank_mask:0xf bound_ctrl:1
	s_and_saveexec_b64 s[8:9], vcc
	v_lshlrev_b32_e32 v53, 4, v145
	v_lshlrev_b32_e32 v54, 1, v146
	v_add3_u32 v53, s86, v53, v54
	v_lshl_or_b32 v19, v19, 16, v52
	ds_write_b32 v53, v19
	s_or_b64 exec, exec, s[8:9]
	v_mul_f32_e32 v19, 0xbfb8aa3b, v144
	v_exp_f32_e32 v19, v19
	s_waitcnt lgkmcnt(0)
	s_barrier
	v_add_f32_e32 v19, 1.0, v19
	v_rcp_f32_e32 v52, v19
	v_lshl_add_u32 v19, v133, 4, 0
	v_add_u32_e32 v178, 0x12500, v19
	s_lshl_b32 s42, s36, 21
	v_pk_mul_f32 v[38:39], v[52:53], v[38:39] op_sel_hi:[0,1]
	v_pk_mul_f32 v[36:37], v[52:53], v[36:37] op_sel_hi:[0,1]
	ds_write_b128 v178, v[36:39]
	v_pk_mul_f32 v[38:39], v[52:53], v[50:51] op_sel_hi:[0,1]
	v_pk_mul_f32 v[36:37], v[52:53], v[48:49] op_sel_hi:[0,1]
	ds_write_b128 v178, v[36:39] offset:8192
	v_mul_f32_e32 v36, 0xbfb8aa3b, v143
	v_exp_f32_e32 v36, v36
	v_pk_mul_f32 v[34:35], v[52:53], v[34:35] op_sel_hi:[0,1]
	v_pk_mul_f32 v[32:33], v[52:53], v[32:33] op_sel_hi:[0,1]
	ds_write_b128 v178, v[32:35] offset:16384
	v_add_f32_e32 v32, 1.0, v36
	v_rcp_f32_e32 v36, v32
	v_pk_mul_f32 v[34:35], v[52:53], v[42:43] op_sel_hi:[0,1]
	v_pk_mul_f32 v[32:33], v[52:53], v[40:41] op_sel_hi:[0,1]
	ds_write_b128 v178, v[32:35] offset:24576
	v_pk_mul_f32 v[22:23], v[36:37], v[22:23] op_sel_hi:[0,1]
	v_pk_mul_f32 v[20:21], v[36:37], v[20:21] op_sel_hi:[0,1]
	v_pk_mul_f32 v[26:27], v[36:37], v[26:27] op_sel_hi:[0,1]
	v_pk_mul_f32 v[24:25], v[36:37], v[24:25] op_sel_hi:[0,1]
	ds_write_b128 v178, v[20:23] offset:57344
	v_and_b32_e32 v20, 12, v133
	v_pk_mul_f32 v[30:31], v[36:37], v[30:31] op_sel_hi:[0,1]
	v_pk_mul_f32 v[28:29], v[36:37], v[28:29] op_sel_hi:[0,1]
	ds_write_b128 v178, v[24:27] offset:40960
	v_pk_mul_f32 v[26:27], v[36:37], v[46:47] op_sel_hi:[0,1]
	v_pk_mul_f32 v[24:25], v[36:37], v[44:45] op_sel_hi:[0,1]
	v_lshlrev_b32_e32 v21, 7, v141
	v_lshlrev_b32_e32 v20, 2, v20
	ds_write_b128 v178, v[28:31] offset:32768
	ds_write_b128 v178, v[24:27] offset:49152
	v_add3_u32 v20, s86, v21, v20
	ds_read_b128 v[32:35], v20
	ds_read_b128 v[36:39], v20 offset:64
	s_cmp_gt_i32 s0, -1
	s_cselect_b64 s[28:29], -1, 0
	s_add_u32 s43, s67, s42
	s_addc_u32 s44, s72, 0
	s_cmp_lt_i32 s0, 0
	s_waitcnt lgkmcnt(0)
	s_barrier
	s_cbranch_scc1 .LBB0_2645
	s_cmp_gt_i32 s0, 0
	s_cselect_b64 s[30:31], -1, 0
	s_cmp_lt_i32 s0, 1
	s_cbranch_scc0 .LBB0_2646

; template <bool SEL> ...
;     ...
;     for (int pi = 0; pi < 2; ++pi) if (pi < n) { const unsigned char* blk = KV + (size_t)(jhi - pi) * SLOTB; dma_block(lds3, pi, wu, blk, soff, blk + 8192, soff); }
;     for (int it0 = 0; it0 < n; it0 += 2) {
;         ring_wait_bar(0);
.LBB0_2646:
	v_mul_i32_i24_e32 v20, -8, v142
	s_andn2_b64 vcc, exec, s[28:29]
	v_add3_u32 v179, v20, v135, v132
	s_cbranch_vccz .LBB0_2473
